# v10
# speedup vs baseline: 1.0206x; 1.0011x over previous
.LBB0_62:
	v_cmp_gt_f32_e32 vcc, 1.0, v253
	s_cbranch_vccz .LBB0_66
	s_and_saveexec_b64 s[10:11], s[8:9]
	ds_write_b32 v191, v253 offset:128
	s_or_b64 exec, exec, s[10:11]
	s_waitcnt lgkmcnt(0)
	v_add_u32_e32 v251, s59, v152
	ds_read_b128 v[212:215], v251 offset:224
	ds_read_b128 v[216:219], v251 offset:192
	ds_read_b128 v[220:223], v251 offset:160
	ds_read_b128 v[224:227], v251 offset:128
	s_waitcnt lgkmcnt(3)
	v_pk_mul_f32 v[12:13], v[12:13], v[212:213]
	s_waitcnt lgkmcnt(2)
	v_pk_mul_f32 v[8:9], v[8:9], v[216:217]
	s_waitcnt lgkmcnt(1)
	v_pk_mul_f32 v[4:5], v[4:5], v[220:221]
	v_pk_mul_f32 v[14:15], v[14:15], v[214:215]
	v_pk_mul_f32 v[10:11], v[10:11], v[218:219]
	v_pk_mul_f32 v[6:7], v[6:7], v[222:223]
	s_waitcnt lgkmcnt(0)
	v_pk_mul_f32 v[2:3], v[2:3], v[226:227]
	v_pk_mul_f32 v[0:1], v[0:1], v[224:225]
	v_pk_mul_f32 v[28:29], v[28:29], v[212:213]
	v_pk_mul_f32 v[24:25], v[24:25], v[216:217]
	v_pk_mul_f32 v[20:21], v[20:21], v[220:221]
	v_pk_mul_f32 v[30:31], v[30:31], v[214:215]
	v_pk_mul_f32 v[26:27], v[26:27], v[218:219]
	v_pk_mul_f32 v[22:23], v[22:23], v[222:223]
	v_pk_mul_f32 v[18:19], v[18:19], v[226:227]
	v_pk_mul_f32 v[16:17], v[16:17], v[224:225]
	v_pk_mul_f32 v[44:45], v[44:45], v[212:213]
	v_pk_mul_f32 v[40:41], v[40:41], v[216:217]
	v_pk_mul_f32 v[36:37], v[36:37], v[220:221]
	v_pk_mul_f32 v[46:47], v[46:47], v[214:215]
	v_pk_mul_f32 v[42:43], v[42:43], v[218:219]
	v_pk_mul_f32 v[38:39], v[38:39], v[222:223]
	v_pk_mul_f32 v[34:35], v[34:35], v[226:227]
	v_pk_mul_f32 v[32:33], v[32:33], v[224:225]
	v_pk_mul_f32 v[60:61], v[60:61], v[212:213]
	v_pk_mul_f32 v[56:57], v[56:57], v[216:217]
	v_pk_mul_f32 v[52:53], v[52:53], v[220:221]
	v_pk_mul_f32 v[62:63], v[62:63], v[214:215]
	v_pk_mul_f32 v[58:59], v[58:59], v[218:219]
	v_pk_mul_f32 v[54:55], v[54:55], v[222:223]
	v_pk_mul_f32 v[50:51], v[50:51], v[226:227]
	v_pk_mul_f32 v[48:49], v[48:49], v[224:225]
	v_mov_b32_e32 v253, 1.0
	ds_read_b128 v[228:231], v193 offset:8192
	ds_read_b128 v[224:227], v193 offset:12288

.LBB0_67:
	s_barrier
	s_add_i32 s10, s49, 0
	s_waitcnt vmcnt(0)
	v_add_u32_e32 v189, s10, v173
	ds_write_b128 v189, v[128:131]
	v_add_u32_e32 v128, s10, v174
	ds_write_b128 v128, v[124:127]
	ds_write_b128 v189, v[112:115] offset:16384
	ds_write_b128 v128, v[116:119] offset:16384
	v_lshl_add_u32 v124, s48, 14, v175
	v_cmp_gt_f32_e32 vcc, 1.0, v253
	ds_write_b128 v124, v[132:135]
	ds_write_b128 v124, v[120:123] offset:8192
	s_cbranch_vccz .LBB0_71
	s_and_saveexec_b64 s[10:11], s[8:9]
	ds_write_b32 v191, v253 offset:128
	s_or_b64 exec, exec, s[10:11]
	s_waitcnt lgkmcnt(0)
	v_add_u32_e32 v251, s59, v152
	ds_read_b128 v[212:215], v251 offset:224
	ds_read_b128 v[216:219], v251 offset:192
	ds_read_b128 v[220:223], v251 offset:160
	ds_read_b128 v[224:227], v251 offset:128
	s_waitcnt lgkmcnt(3)
	v_pk_mul_f32 v[12:13], v[12:13], v[212:213]
	s_waitcnt lgkmcnt(2)
	v_pk_mul_f32 v[8:9], v[8:9], v[216:217]
	s_waitcnt lgkmcnt(1)
	v_pk_mul_f32 v[4:5], v[4:5], v[220:221]
	v_pk_mul_f32 v[14:15], v[14:15], v[214:215]
	v_pk_mul_f32 v[10:11], v[10:11], v[218:219]
	v_pk_mul_f32 v[6:7], v[6:7], v[222:223]
	s_waitcnt lgkmcnt(0)
	v_pk_mul_f32 v[2:3], v[2:3], v[226:227]
	v_pk_mul_f32 v[0:1], v[0:1], v[224:225]
	v_pk_mul_f32 v[28:29], v[28:29], v[212:213]
	v_pk_mul_f32 v[24:25], v[24:25], v[216:217]
	v_pk_mul_f32 v[20:21], v[20:21], v[220:221]
	v_pk_mul_f32 v[30:31], v[30:31], v[214:215]
	v_pk_mul_f32 v[26:27], v[26:27], v[218:219]
	v_pk_mul_f32 v[22:23], v[22:23], v[222:223]
	v_pk_mul_f32 v[18:19], v[18:19], v[226:227]
	v_pk_mul_f32 v[16:17], v[16:17], v[224:225]
	v_pk_mul_f32 v[44:45], v[44:45], v[212:213]
	v_pk_mul_f32 v[40:41], v[40:41], v[216:217]
	v_pk_mul_f32 v[36:37], v[36:37], v[220:221]
	v_pk_mul_f32 v[46:47], v[46:47], v[214:215]
	v_pk_mul_f32 v[42:43], v[42:43], v[218:219]
	v_pk_mul_f32 v[38:39], v[38:39], v[222:223]
	v_pk_mul_f32 v[34:35], v[34:35], v[226:227]
	v_pk_mul_f32 v[32:33], v[32:33], v[224:225]
	v_pk_mul_f32 v[60:61], v[60:61], v[212:213]
	v_pk_mul_f32 v[56:57], v[56:57], v[216:217]
	v_pk_mul_f32 v[52:53], v[52:53], v[220:221]
	v_pk_mul_f32 v[62:63], v[62:63], v[214:215]
	v_pk_mul_f32 v[58:59], v[58:59], v[218:219]
	v_pk_mul_f32 v[54:55], v[54:55], v[222:223]
	v_pk_mul_f32 v[50:51], v[50:51], v[226:227]
	v_pk_mul_f32 v[48:49], v[48:49], v[224:225]
	v_mov_b32_e32 v253, 1.0

.LBB0_103:
	s_barrier
	s_add_i32 s10, s42, 0
	s_waitcnt vmcnt(0)
	v_add_u32_e32 v189, s10, v178
	ds_write_b128 v189, v[128:131]
	v_add_u32_e32 v128, s10, v179
	ds_write_b128 v128, v[124:127]
	ds_write_b128 v189, v[112:115] offset:16384
	ds_write_b128 v128, v[116:119] offset:16384
	v_lshl_add_u32 v124, s25, 14, v177
	v_cmp_gt_f32_e32 vcc, 1.0, v253
	ds_write_b128 v124, v[132:135]
	ds_write_b128 v124, v[120:123] offset:8192
	s_cbranch_vccz .LBB0_107
	s_and_saveexec_b64 s[10:11], s[8:9]
	ds_write_b32 v191, v253 offset:128
	s_or_b64 exec, exec, s[10:11]
	s_waitcnt lgkmcnt(0)
	v_add_u32_e32 v251, s59, v152
	ds_read_b128 v[212:215], v251 offset:224
	ds_read_b128 v[216:219], v251 offset:192
	ds_read_b128 v[220:223], v251 offset:160
	ds_read_b128 v[224:227], v251 offset:128
	s_waitcnt lgkmcnt(3)
	v_pk_mul_f32 v[12:13], v[12:13], v[212:213]
	s_waitcnt lgkmcnt(2)
	v_pk_mul_f32 v[8:9], v[8:9], v[216:217]
	s_waitcnt lgkmcnt(1)
	v_pk_mul_f32 v[4:5], v[4:5], v[220:221]
	v_pk_mul_f32 v[14:15], v[14:15], v[214:215]
	v_pk_mul_f32 v[10:11], v[10:11], v[218:219]
	v_pk_mul_f32 v[6:7], v[6:7], v[222:223]
	s_waitcnt lgkmcnt(0)
	v_pk_mul_f32 v[2:3], v[2:3], v[226:227]
	v_pk_mul_f32 v[0:1], v[0:1], v[224:225]
	v_pk_mul_f32 v[28:29], v[28:29], v[212:213]
	v_pk_mul_f32 v[24:25], v[24:25], v[216:217]
	v_pk_mul_f32 v[20:21], v[20:21], v[220:221]
	v_pk_mul_f32 v[30:31], v[30:31], v[214:215]
	v_pk_mul_f32 v[26:27], v[26:27], v[218:219]
	v_pk_mul_f32 v[22:23], v[22:23], v[222:223]
	v_pk_mul_f32 v[18:19], v[18:19], v[226:227]
	v_pk_mul_f32 v[16:17], v[16:17], v[224:225]
	v_pk_mul_f32 v[44:45], v[44:45], v[212:213]
	v_pk_mul_f32 v[40:41], v[40:41], v[216:217]
	v_pk_mul_f32 v[36:37], v[36:37], v[220:221]
	v_pk_mul_f32 v[46:47], v[46:47], v[214:215]
	v_pk_mul_f32 v[42:43], v[42:43], v[218:219]
	v_pk_mul_f32 v[38:39], v[38:39], v[222:223]
	v_pk_mul_f32 v[34:35], v[34:35], v[226:227]
	v_pk_mul_f32 v[32:33], v[32:33], v[224:225]
	v_pk_mul_f32 v[60:61], v[60:61], v[212:213]
	v_pk_mul_f32 v[56:57], v[56:57], v[216:217]
	v_pk_mul_f32 v[52:53], v[52:53], v[220:221]
	v_pk_mul_f32 v[62:63], v[62:63], v[214:215]
	v_pk_mul_f32 v[58:59], v[58:59], v[218:219]
	v_pk_mul_f32 v[54:55], v[54:55], v[222:223]
	v_pk_mul_f32 v[50:51], v[50:51], v[226:227]
	v_pk_mul_f32 v[48:49], v[48:49], v[224:225]
	v_mov_b32_e32 v253, 1.0

.LBB0_122:
	s_add_i32 s8, s40, s36
	ds_read_b128 v[160:163], v215 offset:49152
	ds_read_b128 v[164:167], v215 offset:57344
	v_xor_b32_e32 v80, 0x80000000, v235
	v_mov_b32_e32 v81, v80
	v_mov_b32_e32 v82, v80
	v_mov_b32_e32 v83, v80
	v_mov_b32_e32 v84, v80
	v_mov_b32_e32 v85, v80
	v_mov_b32_e32 v86, v80
	v_mov_b32_e32 v87, v80
	v_mov_b32_e32 v88, v80
	v_mov_b32_e32 v89, v80
	v_mov_b32_e32 v90, v80
	v_mov_b32_e32 v91, v80
	v_mov_b32_e32 v92, v80
	v_mov_b32_e32 v93, v80
	v_mov_b32_e32 v94, v80
	v_mov_b32_e32 v95, v80
	s_add_i32 s9, 0, 0x12000
	v_exp_f32_e32 v78, v78
	s_waitcnt lgkmcnt(1)
	v_mfma_f32_32x32x16_bf16 v[96:111], v[160:163], v[128:131], v[80:95]
	v_exp_f32_e32 v79, v79
	v_exp_f32_e32 v76, v76
	v_exp_f32_e32 v77, v77
	v_exp_f32_e32 v74, v74
	v_exp_f32_e32 v75, v75
	s_waitcnt lgkmcnt(0)
	v_mfma_f32_32x32x16_bf16 v[80:95], v[164:167], v[128:131], v[80:95]
	ds_read_b128 v[160:163], v216 offset:49152
	ds_read_b128 v[164:167], v216 offset:57344
	s_waitcnt lgkmcnt(1)
	v_mfma_f32_32x32x16_bf16 v[96:111], v[160:163], v[132:135], v[96:111]
	ds_read_b128 v[160:163], v217 offset:49152
	v_add_f32_e32 v201, 0, v120
	v_add_f32_e32 v201, v121, v201
	s_waitcnt lgkmcnt(1)
	v_mfma_f32_32x32x16_bf16 v[80:95], v[164:167], v[132:135], v[80:95]
	ds_read_b128 v[164:167], v217 offset:57344
	v_add_f32_e32 v201, v122, v201
	v_add_f32_e32 v201, v124, v201
	s_waitcnt lgkmcnt(1)
	v_mfma_f32_32x32x16_bf16 v[96:111], v[160:163], v[136:139], v[96:111]
	ds_read_b128 v[160:163], v218 offset:49152
	v_add_f32_e32 v201, v125, v201
	v_add_f32_e32 v201, v127, v201
	s_waitcnt lgkmcnt(1)
	v_mfma_f32_32x32x16_bf16 v[80:95], v[164:167], v[136:139], v[80:95]
	ds_read_b128 v[164:167], v218 offset:57344
	v_add_f32_e32 v201, v123, v201
	v_add_f32_e32 v201, v126, v201
	s_waitcnt lgkmcnt(1)
	v_mfma_f32_32x32x16_bf16 v[96:111], v[160:163], v[140:143], v[96:111]
	ds_read_b128 v[160:163], v219 offset:49152
	v_add_f32_e32 v201, v112, v201
	v_add_f32_e32 v201, v114, v201
	s_waitcnt lgkmcnt(1)
	v_mfma_f32_32x32x16_bf16 v[80:95], v[164:167], v[140:143], v[80:95]
	ds_read_b128 v[164:167], v219 offset:57344
	v_add_f32_e32 v201, v115, v201
	v_add_f32_e32 v201, v118, v201
	s_waitcnt lgkmcnt(1)
	v_mfma_f32_32x32x16_bf16 v[96:111], v[160:163], v[144:147], v[96:111]
	ds_read_b128 v[160:163], v220 offset:49152
	v_add_f32_e32 v201, v113, v201
	v_add_f32_e32 v201, v116, v201
	s_waitcnt lgkmcnt(1)
	v_mfma_f32_32x32x16_bf16 v[80:95], v[164:167], v[144:147], v[80:95]
	ds_read_b128 v[164:167], v220 offset:57344
	v_add_f32_e32 v201, v117, v201
	v_add_f32_e32 v201, v119, v201
	s_waitcnt lgkmcnt(1)
	v_mfma_f32_32x32x16_bf16 v[96:111], v[160:163], v[148:151], v[96:111]
	ds_read_b128 v[160:163], v221 offset:49152
	v_add_f32_e32 v201, v78, v201
	v_add_f32_e32 v201, v79, v201
	s_waitcnt lgkmcnt(1)
	v_mfma_f32_32x32x16_bf16 v[80:95], v[164:167], v[148:151], v[80:95]
	ds_read_b128 v[164:167], v221 offset:57344
	v_add_f32_e32 v201, v76, v201
	v_add_f32_e32 v201, v77, v201
	s_waitcnt lgkmcnt(1)
	v_mfma_f32_32x32x16_bf16 v[96:111], v[160:163], v[152:155], v[96:111]
	ds_read_b128 v[160:163], v222 offset:49152
	v_add_f32_e32 v201, v74, v201
	v_add_f32_e32 v201, v75, v201
	s_waitcnt lgkmcnt(1)
	v_mfma_f32_32x32x16_bf16 v[80:95], v[164:167], v[152:155], v[80:95]
	ds_read_b128 v[164:167], v222 offset:57344
	ds_read_b128 v[168:171], v224 offset:8192
	ds_read_b128 v[172:175], v224 offset:12288
	ds_read_b128 v[176:179], v225
	s_waitcnt lgkmcnt(4)
	v_mfma_f32_32x32x16_bf16 v[96:111], v[160:163], v[156:159], v[96:111]
	ds_read_b128 v[160:163], v227 offset:8192
	s_waitcnt lgkmcnt(4)
	v_mfma_f32_32x32x16_bf16 v[80:95], v[164:167], v[156:159], v[80:95]
	ds_read_b128 v[164:167], v227 offset:12288
	s_waitcnt lgkmcnt(2)
	v_mfma_f32_32x32x16_bf16 v[96:111], v[168:171], v[176:179], v[96:111]
	v_mfma_f32_32x32x16_bf16 v[80:95], v[172:175], v[176:179], v[80:95]
	ds_read_b128 v[168:171], v228
	ds_read_b128 v[172:175], v230 offset:8192
	ds_read_b128 v[176:179], v230 offset:12288
	s_waitcnt lgkmcnt(2)
	v_mfma_f32_32x32x16_bf16 v[96:111], v[160:163], v[168:171], v[96:111]
	v_mfma_f32_32x32x16_bf16 v[80:95], v[164:167], v[168:171], v[80:95]
	ds_read_b128 v[160:163], v231
	ds_read_b128 v[164:167], v233 offset:8192
	ds_read_b128 v[168:171], v233 offset:12288
	s_waitcnt lgkmcnt(2)
	v_mfma_f32_32x32x16_bf16 v[96:111], v[172:175], v[160:163], v[96:111]
	v_mfma_f32_32x32x16_bf16 v[80:95], v[176:179], v[160:163], v[80:95]
	ds_read_b128 v[172:175], v234
	s_waitcnt lgkmcnt(0)
	v_mfma_f32_32x32x16_bf16 v[96:111], v[164:167], v[172:175], v[96:111]
	v_exp_f32_e32 v160, v72
	v_exp_f32_e32 v161, v73
	v_exp_f32_e32 v162, v70
	v_exp_f32_e32 v163, v71
	v_cvt_pk_bf16_f32 v70, v113, v116
	v_cvt_pk_bf16_f32 v71, v117, v119
	v_cvt_pk_bf16_f32 v72, v78, v79
	v_mfma_f32_32x32x16_bf16 v[80:95], v[168:171], v[172:175], v[80:95]
	v_exp_f32_e32 v168, v64
	v_exp_f32_e32 v164, v68
	v_add_f32_e32 v64, v160, v201
	v_exp_f32_e32 v165, v69
	v_add_f32_e32 v64, v161, v64
	v_exp_f32_e32 v166, v66
	v_add_f32_e32 v64, v162, v64
	v_exp_f32_e32 v167, v67
	v_add_f32_e32 v64, v163, v64
	v_add_f32_e32 v64, v164, v64
	v_exp_f32_e32 v169, v65
	v_add_f32_e32 v64, v165, v64
	v_add_f32_e32 v64, v166, v64
	v_add_f32_e32 v64, v167, v64
	v_add_f32_e32 v64, v168, v64
	v_add_f32_e32 v242, v169, v64
	v_mov_b32_e32 v243, v242
	v_cvt_pk_bf16_f32 v64, v120, v121
	v_cvt_pk_bf16_f32 v65, v122, v124
	v_cvt_pk_bf16_f32 v66, v125, v127
	v_cvt_pk_bf16_f32 v67, v123, v126
	v_cvt_pk_bf16_f32 v68, v112, v114
	v_cvt_pk_bf16_f32 v69, v115, v118
	v_cvt_pk_bf16_f32 v73, v76, v77
	v_cvt_pk_bf16_f32 v74, v74, v75
	v_cvt_pk_bf16_f32 v75, v160, v161
	v_cvt_pk_bf16_f32 v76, v162, v163
	v_cvt_pk_bf16_f32 v77, v164, v165
	v_cvt_pk_bf16_f32 v78, v166, v167
	v_cvt_pk_bf16_f32 v79, v168, v169
	v_permlane32_swap_b32_e32 v242, v243
	v_permlane32_swap_b32_e32 v64, v66
	v_permlane32_swap_b32_e32 v65, v67
	v_permlane32_swap_b32_e32 v68, v70
	v_permlane32_swap_b32_e32 v69, v71
	v_permlane32_swap_b32_e32 v72, v74
	v_permlane32_swap_b32_e32 v73, v75
	v_permlane32_swap_b32_e32 v76, v78
	v_permlane32_swap_b32_e32 v77, v79
	s_cmp_eq_u32 s8, 0
	s_cselect_b64 s[8:9], -1, 0
	s_add_u32 s41, s18, s38
	s_addc_u32 s42, s19, s39
	s_add_u32 s20, s18, s10
	s_addc_u32 s21, s19, s11
	s_and_b64 vcc, exec, s[8:9]
	s_cbranch_vccnz .Lmla_sl_last
	s_add_u32 s22, s41, 0x64c2400
	s_addc_u32 s23, s42, 0
	s_add_u32 s44, s41, 0x64c2500
	s_addc_u32 s45, s42, 0
	global_load_dwordx4 v[160:163], v190, s[44:45]
	global_load_dwordx4 v[164:167], v192, s[44:45]
	global_load_dwordx4 v[168:171], v190, s[22:23]
	global_load_dwordx4 v[172:175], v192, s[22:23]
	s_add_u32 s44, s20, 0x28f26400
	s_addc_u32 s45, s21, 0
	global_load_dwordx4 v[176:179], v194, s[44:45]
	s_branch .Lmla_sl_merge
